# seam 0 barrier also publishes the per-XCD census so the first two-level barrier skips its census pass
# speedup vs baseline: 1.0115x; 1.0021x over previous
; __device__ __forceinline__ unsigned xb_ld(unsigned* p)              { return __hip_atomic_load(p, __ATOMIC_RELAXED, __HIP_MEMORY_SCOPE_AGENT); }
; __device__ __forceinline__ void xcd_barrier_complete(unsigned* bar, unsigned x, unsigned& nloc, unsigned& nx) {
;     const unsigned G = gridDim.x * gridDim.y * gridDim.z;
;     unsigned sum, cnt, mine, sp = 0u;
;     for (;;) {
;         sum = 0u; cnt = 0u; mine = 0u;
; #pragma unroll
;         for (unsigned j = 0; j < 16; ++j) { const unsigned c = xb_ld(&bar[XB_XCNT(j)]); sum += c; cnt += (c > 0u) ? 1u : 0u; mine = (j == x) ? c : mine; }
;         if (sum == G) break;
;         __builtin_amdgcn_s_sleep(1);
;         if ((++sp & 255u) == 0u) { if (xb_ld(&bar[XB_TMO])) break; if (sp > XB_SPIN_CAP) { atomicAdd(&bar[XB_TMO], 1u); break; } }
;     }
;     nloc = mine > 0u ? mine : 1u; nx = cnt > 0u ? cnt : 1u;
; }
.Lg0_census:
	s_mov_b32 s12, 0
	s_mov_b32 s13, 0
	s_mov_b32 s14, 0
	s_mov_b32 s17, 0
.Lg0_cj:
	s_lshl_b32 s15, s12, 8
	s_add_i32 s15, s15, 0x400
	v_mov_b32_e32 v0, s15
	global_load_dword v1, v0, s[4:5] sc1
	s_waitcnt vmcnt(0)
	v_readfirstlane_b32 s16, v1
	s_add_i32 s13, s13, s16
	s_cmp_eq_u32 s12, s10
	s_cselect_b32 s14, s16, s14
	s_cmp_lg_u32 s16, 0
	s_cselect_b32 s9, 1, 0
	s_add_i32 s17, s17, s9
	s_add_i32 s12, s12, 1
	s_cmp_lt_u32 s12, 16
	s_cbranch_scc1 .Lg0_cj
	s_cmp_eq_u32 s13, s34
	s_cbranch_scc1 .Lg0_pub
	s_sleep 1
	s_add_i32 s11, s11, 1
	s_cmp_lt_u32 s11, 0x4000
	s_cbranch_scc1 .Lg0_census
	s_branch .Lg0_arrive
.Lg0_pub:
	v_mov_b32_e32 v0, 0x25100
	v_mov_b32_e32 v2, s14
	v_mov_b32_e32 v3, s17
	ds_write_b64 v0, v[2:3]
